# v64 + code placement: every 16/32-MFMA burst placed at byte phase 4 mod 8 (s_nop pads in load segments)
# speedup vs baseline: 1.0043x; 1.0043x over previous
; #define PG8_STAGE(bufoff, gbase, voff) do { _Pragma("unroll") for (int _i = 0; _i < 2; ++_i) \
;         __builtin_amdgcn_global_load_lds((const unsigned*)((const char*)(gbase) + (voff)[_i]), (PG8_LAS unsigned*)(lds + (bufoff) + ldsw + _i * 8192), 16, 0, 0); } while (0)
; #define PG8_STAGE_NT(bufoff, gbase, voff) do { _Pragma("unroll") for (int _i = 0; _i < 2; ++_i) \
;         __builtin_amdgcn_global_load_lds((const unsigned*)((const char*)(gbase) + (voff)[_i]), (PG8_LAS unsigned*)(lds + (bufoff) + ldsw + _i * 8192), 16, 0, PG8_B_AUX); } while (0)
; #define PG8_LDA(dst, b, h) do { _Pragma("unroll") for (int m = 0; m < 4; ++m) _Pragma("unroll") for (int k = 0; k < 2; ++k) dst[m][k] = *(const PG8_LAS bf16x8*)(lds + PG8_SA(b, h) + aoff + m * 2048 + k * 1024); } while (0)
; #define PG8_LDB(dst, b, h) do { _Pragma("unroll") for (int n = 0; n < 2; ++n) _Pragma("unroll") for (int k = 0; k < 2; ++k) dst[n][k] = *(const PG8_LAS bf16x8*)(lds + PG8_SB(b, h) + boff + n * 2048 + k * 1024); } while (0)
; #define PG8_WAIT_V(n) asm volatile("s_waitcnt vmcnt(" #n ")" ::: "memory")
; #define PG8_WAIT_L(n) asm volatile("s_waitcnt lgkmcnt(" #n ")" ::: "memory")
; #define PG8_BAR __builtin_amdgcn_s_barrier()
; #define PG8_SCHED __builtin_amdgcn_sched_barrier(0)
; template <class Epi, class Sched, bool ALIGN_EPI = false, bool SP2 = false>
; __device__ __forceinline__ void gemm_phase(PG8_LAS unsigned char* lds, const Gemm g, const Sched& S, const Epi& E, int wid) {
;     ...
;             const bool last = (t == nt - 2);
;             const char* a1 = cA + (size_t)(t + 1) * kstep;
;             const char* a2 = last ? nA : cA + (size_t)(t + 2) * kstep; const char* b2 = last ? nB : cB + (size_t)(t + 2) * kstep;
;             const char* a3 = a2 + kstep; const char* b3 = b2 + kstep;
;             if (last && has_next) S.a_ready(nxt);
;             if constexpr (SP2) {
;             PG8_LDB(B0, 0, 0); PG8_LDB(B1, 0, 1); PG8_SCHED; PG8_LDA(At, 0, 0); PG8_STAGE(PG8_SA(1, 1), a1 + hstepA, voffA);
;             PG8_WAIT_V(8); PG8_WAIT_L(0); PG8_BAR; PG8_MMA(0, 0, At, B0); PG8_MMA(0, 1, At, B1); PG8_BAR; PG8_SCHED;
;             PG8_LDA(At, 0, 1); PG8_STAGE_NT(PG8_SB(0, 0), b2, voffB); PG8_STAGE_NT(PG8_SB(0, 1), b2 + hstepB, voffB); PG8_STAGE(PG8_SA(0, 0), a2, voffA);
;             PG8_WAIT_V(8); PG8_WAIT_L(0); PG8_BAR; PG8_MMA(1, 0, At, B0); PG8_MMA(1, 1, At, B1); PG8_BAR; PG8_SCHED;
.LBB0_233:
	ds_read_b128 v[144:147], v155
	ds_read_b128 v[148:151], v155 offset:1024
	ds_read_b128 v[160:163], v155 offset:2048
	ds_read_b128 v[164:167], v155 offset:3072
	ds_read_b128 v[168:171], v156
	ds_read_b128 v[172:175], v156 offset:1024
	ds_read_b128 v[176:179], v156 offset:2048
	ds_read_b128 v[180:183], v156 offset:3072
	s_add_u32 s4, s48, 0x100
	s_addc_u32 s5, s49, 0
	s_add_u32 s98, s48, 0x80
	s_addc_u32 s99, s49, 0
	s_add_u32 s100, s48, 0x104080
	s_addc_u32 s101, s49, 0
	s_cmp_eq_u32 s66, 60
	s_cselect_b32 s53, s45, s5
	s_cselect_b32 s52, s44, s4
	s_cselect_b32 s51, s47, s65
	s_cselect_b32 s50, s46, s64
	s_add_i32 m0, s23, 0xc000
	ds_read_b128 v[184:187], v157
	ds_read_b128 v[188:191], v157 offset:1024
	ds_read_b128 v[192:195], v157 offset:2048
	ds_read_b128 v[196:199], v157 offset:3072
	ds_read_b128 v[200:203], v157 offset:4096
	ds_read_b128 v[204:207], v157 offset:5120
	ds_read_b128 v[208:211], v157 offset:6144
	ds_read_b128 v[212:215], v157 offset:7168
	global_load_lds_dwordx4 v134, s[100:101]
	s_add_i32 m0, s23, 0xe000
	s_nop 0
	global_load_lds_dwordx4 v130, s[100:101]
	s_mov_b32 m0, s55
	s_nop 0
	global_load_lds_dwordx4 v134, s[98:99]
	s_mov_b32 m0, s56
	s_nop 0
	global_load_lds_dwordx4 v130, s[98:99]
	s_waitcnt vmcnt(8)
	s_waitcnt lgkmcnt(0)
	s_barrier
	s_waitcnt lgkmcnt(0)
	v_mfma_f32_16x16x32_bf16 v[112:115], v[144:147], v[184:187], v[112:115]
	v_mfma_f32_16x16x32_bf16 v[108:111], v[160:163], v[184:187], v[108:111]
	v_mfma_f32_16x16x32_bf16 v[104:107], v[144:147], v[192:195], v[104:107]
	v_mfma_f32_16x16x32_bf16 v[100:103], v[160:163], v[192:195], v[100:103]
	v_mfma_f32_16x16x32_bf16 v[92:95], v[144:147], v[200:203], v[92:95]
	v_mfma_f32_16x16x32_bf16 v[84:87], v[160:163], v[200:203], v[84:87]
	v_mfma_f32_16x16x32_bf16 v[76:79], v[144:147], v[208:211], v[76:79]
	v_mfma_f32_16x16x32_bf16 v[68:71], v[160:163], v[208:211], v[68:71]
	v_mfma_f32_16x16x32_bf16 v[112:115], v[148:151], v[188:191], v[112:115]
	v_mfma_f32_16x16x32_bf16 v[108:111], v[164:167], v[188:191], v[108:111]
	v_mfma_f32_16x16x32_bf16 v[104:107], v[148:151], v[196:199], v[104:107]
	v_mfma_f32_16x16x32_bf16 v[100:103], v[164:167], v[196:199], v[100:103]
	v_mfma_f32_16x16x32_bf16 v[92:95], v[148:151], v[204:207], v[92:95]
	v_mfma_f32_16x16x32_bf16 v[84:87], v[164:167], v[204:207], v[84:87]
	v_mfma_f32_16x16x32_bf16 v[76:79], v[148:151], v[212:215], v[76:79]
	v_mfma_f32_16x16x32_bf16 v[68:71], v[164:167], v[212:215], v[68:71]
	v_mfma_f32_16x16x32_bf16 v[124:127], v[168:171], v[184:187], v[124:127]
	v_mfma_f32_16x16x32_bf16 v[120:123], v[176:179], v[184:187], v[120:123]
	v_mfma_f32_16x16x32_bf16 v[116:119], v[168:171], v[192:195], v[116:119]
	v_mfma_f32_16x16x32_bf16 v[96:99], v[176:179], v[192:195], v[96:99]
	v_mfma_f32_16x16x32_bf16 v[88:91], v[168:171], v[200:203], v[88:91]
	v_mfma_f32_16x16x32_bf16 v[80:83], v[176:179], v[200:203], v[80:83]
	v_mfma_f32_16x16x32_bf16 v[72:75], v[168:171], v[208:211], v[72:75]
	v_mfma_f32_16x16x32_bf16 v[64:67], v[176:179], v[208:211], v[64:67]
	v_mfma_f32_16x16x32_bf16 v[124:127], v[172:175], v[188:191], v[124:127]
	v_mfma_f32_16x16x32_bf16 v[120:123], v[180:183], v[188:191], v[120:123]
	v_mfma_f32_16x16x32_bf16 v[116:119], v[172:175], v[196:199], v[116:119]
	v_mfma_f32_16x16x32_bf16 v[96:99], v[180:183], v[196:199], v[96:99]
	v_mfma_f32_16x16x32_bf16 v[88:91], v[172:175], v[204:207], v[88:91]
	v_mfma_f32_16x16x32_bf16 v[80:83], v[180:183], v[204:207], v[80:83]
	v_mfma_f32_16x16x32_bf16 v[72:75], v[172:175], v[212:215], v[72:75]
	v_mfma_f32_16x16x32_bf16 v[64:67], v[180:183], v[212:215], v[64:67]
	s_barrier
	s_add_i32 s48, s58, s17
	s_mov_b32 m0, s48
	ds_read_b128 v[184:187], v157 offset:16384
	ds_read_b128 v[188:191], v157 offset:17408
	ds_read_b128 v[192:195], v157 offset:18432
	ds_read_b128 v[196:199], v157 offset:19456
	ds_read_b128 v[200:203], v157 offset:20480
	ds_read_b128 v[204:207], v157 offset:21504
	ds_read_b128 v[208:211], v157 offset:22528
	ds_read_b128 v[212:215], v157 offset:23552
	global_load_lds_dwordx4 v132, s[50:51]
	s_add_i32 m0, s48, 0x2000
	s_add_u32 s48, s50, 0x104000
	s_addc_u32 s49, s51, 0
	s_add_i32 s67, s59, s17
	global_load_lds_dwordx4 v128, s[50:51]
	s_mov_b32 m0, s67
	s_nop 0
	global_load_lds_dwordx4 v132, s[48:49]
	s_add_i32 m0, s67, 0x2000
	s_nop 0
	global_load_lds_dwordx4 v128, s[48:49]
	s_waitcnt vmcnt(4)
	s_waitcnt lgkmcnt(0)
	s_barrier
	s_waitcnt lgkmcnt(0)
	v_mfma_f32_16x16x32_bf16 v[60:63], v[144:147], v[184:187], v[60:63]
	v_mfma_f32_16x16x32_bf16 v[52:55], v[160:163], v[184:187], v[52:55]
	v_mfma_f32_16x16x32_bf16 v[44:47], v[144:147], v[192:195], v[44:47]
	v_mfma_f32_16x16x32_bf16 v[36:39], v[160:163], v[192:195], v[36:39]
	v_mfma_f32_16x16x32_bf16 v[28:31], v[144:147], v[200:203], v[28:31]
	v_mfma_f32_16x16x32_bf16 v[20:23], v[160:163], v[200:203], v[20:23]
	v_mfma_f32_16x16x32_bf16 v[12:15], v[144:147], v[208:211], v[12:15]
	v_mfma_f32_16x16x32_bf16 v[4:7], v[160:163], v[208:211], v[4:7]
	v_mfma_f32_16x16x32_bf16 v[60:63], v[148:151], v[188:191], v[60:63]
	v_mfma_f32_16x16x32_bf16 v[52:55], v[164:167], v[188:191], v[52:55]
	v_mfma_f32_16x16x32_bf16 v[44:47], v[148:151], v[196:199], v[44:47]
	v_mfma_f32_16x16x32_bf16 v[36:39], v[164:167], v[196:199], v[36:39]
	v_mfma_f32_16x16x32_bf16 v[28:31], v[148:151], v[204:207], v[28:31]
	v_mfma_f32_16x16x32_bf16 v[20:23], v[164:167], v[204:207], v[20:23]
	v_mfma_f32_16x16x32_bf16 v[12:15], v[148:151], v[212:215], v[12:15]
	v_mfma_f32_16x16x32_bf16 v[4:7], v[164:167], v[212:215], v[4:7]
	v_mfma_f32_16x16x32_bf16 v[56:59], v[168:171], v[184:187], v[56:59]
	v_mfma_f32_16x16x32_bf16 v[48:51], v[176:179], v[184:187], v[48:51]
	v_mfma_f32_16x16x32_bf16 v[40:43], v[168:171], v[192:195], v[40:43]
	v_mfma_f32_16x16x32_bf16 v[32:35], v[176:179], v[192:195], v[32:35]
	v_mfma_f32_16x16x32_bf16 v[24:27], v[168:171], v[200:203], v[24:27]
	v_mfma_f32_16x16x32_bf16 v[16:19], v[176:179], v[200:203], v[16:19]
	v_mfma_f32_16x16x32_bf16 v[8:11], v[168:171], v[208:211], v[8:11]
	v_mfma_f32_16x16x32_bf16 v[0:3], v[176:179], v[208:211], v[0:3]
	v_mfma_f32_16x16x32_bf16 v[56:59], v[172:175], v[188:191], v[56:59]
	v_mfma_f32_16x16x32_bf16 v[48:51], v[180:183], v[188:191], v[48:51]
	v_mfma_f32_16x16x32_bf16 v[40:43], v[172:175], v[196:199], v[40:43]
	v_mfma_f32_16x16x32_bf16 v[32:35], v[180:183], v[196:199], v[32:35]
	v_mfma_f32_16x16x32_bf16 v[24:27], v[172:175], v[204:207], v[24:27]
	v_mfma_f32_16x16x32_bf16 v[16:19], v[180:183], v[204:207], v[16:19]
	v_mfma_f32_16x16x32_bf16 v[8:11], v[172:175], v[212:215], v[8:11]
	v_mfma_f32_16x16x32_bf16 v[0:3], v[180:183], v[212:215], v[0:3]
	s_barrier
; #define PG8_STAGE(bufoff, gbase, voff) do { _Pragma("unroll") for (int _i = 0; _i < 2; ++_i) \
;         __builtin_amdgcn_global_load_lds((const unsigned*)((const char*)(gbase) + (voff)[_i]), (PG8_LAS unsigned*)(lds + (bufoff) + ldsw + _i * 8192), 16, 0, 0); } while (0)
; #define PG8_STAGE_NT(bufoff, gbase, voff) do { _Pragma("unroll") for (int _i = 0; _i < 2; ++_i) \
;         __builtin_amdgcn_global_load_lds((const unsigned*)((const char*)(gbase) + (voff)[_i]), (PG8_LAS unsigned*)(lds + (bufoff) + ldsw + _i * 8192), 16, 0, PG8_B_AUX); } while (0)
; #define PG8_LDA(dst, b, h) do { _Pragma("unroll") for (int m = 0; m < 4; ++m) _Pragma("unroll") for (int k = 0; k < 2; ++k) dst[m][k] = *(const PG8_LAS bf16x8*)(lds + PG8_SA(b, h) + aoff + m * 2048 + k * 1024); } while (0)
; #define PG8_LDB(dst, b, h) do { _Pragma("unroll") for (int n = 0; n < 2; ++n) _Pragma("unroll") for (int k = 0; k < 2; ++k) dst[n][k] = *(const PG8_LAS bf16x8*)(lds + PG8_SB(b, h) + boff + n * 2048 + k * 1024); } while (0)
; #define PG8_MMA(ai, bj, At, Bt) do { __builtin_amdgcn_s_setprio(1); _Pragma("unroll") for (int m = 0; m < 4; ++m) _Pragma("unroll") for (int n = 0; n < 2; ++n) _Pragma("unroll") for (int k = 0; k < 2; ++k) \
;         acc[ai][bj][m][n] = __builtin_amdgcn_mfma_f32_16x16x32_bf16(Bt[n][k], At[m][k], acc[ai][bj][m][n], 0, 0, 0); __builtin_amdgcn_s_setprio(0); } while (0)
; #define PG8_WAIT_V(n) asm volatile("s_waitcnt vmcnt(" #n ")" ::: "memory")
; #define PG8_WAIT_L(n) asm volatile("s_waitcnt lgkmcnt(" #n ")" ::: "memory")
; #define PG8_BAR __builtin_amdgcn_s_barrier()
; template <class Epi, class Sched, bool ALIGN_EPI = false, bool SP2 = false>
; __device__ __forceinline__ void gemm_phase(PG8_LAS unsigned char* lds, const Gemm g, const Sched& S, const Epi& E, int wid) {
;     ...
;             PG8_LDB(B0, 1, 0); PG8_LDB(B1, 1, 1); PG8_SCHED; PG8_LDA(At, 1, 0); PG8_STAGE(PG8_SA(0, 1), a2 + hstepA, voffA);
;             PG8_WAIT_V(8); PG8_WAIT_L(0); PG8_BAR; PG8_MMA(0, 0, At, B0); PG8_MMA(0, 1, At, B1); PG8_BAR; PG8_SCHED;
;             PG8_LDA(At, 1, 1); PG8_STAGE_NT(PG8_SB(1, 0), b3, voffB); PG8_STAGE_NT(PG8_SB(1, 1), b3 + hstepB, voffB); PG8_STAGE(PG8_SA(1, 0), a3, voffA);
;             PG8_WAIT_V(8); PG8_WAIT_L(0); PG8_BAR; PG8_MMA(1, 0, At, B0); PG8_MMA(1, 1, At, B1); PG8_BAR; PG8_SCHED;
;     ...
;         if constexpr (ALIGN_EPI) { if (wr == 0) PG8_BAR; }
	s_add_i32 s67, 0, 0x18000
	v_add_u32_e32 v159, s67, v153
	s_add_i32 s68, 0, 0x1c000
	ds_read_b128 v[144:147], v159
	ds_read_b128 v[148:151], v159 offset:1024
	ds_read_b128 v[160:163], v159 offset:2048
	ds_read_b128 v[164:167], v159 offset:3072
	v_add_u32_e32 v159, s68, v153
	ds_read_b128 v[168:171], v159
	ds_read_b128 v[172:175], v159 offset:1024
	ds_read_b128 v[176:179], v159 offset:2048
	ds_read_b128 v[180:183], v159 offset:3072
	s_add_u32 s48, s52, 0x104000
	s_addc_u32 s49, s53, 0
	s_mov_b32 m0, s25
	ds_read_b128 v[184:187], v157 offset:32768
	ds_read_b128 v[188:191], v157 offset:33792
	ds_read_b128 v[192:195], v157 offset:34816
	ds_read_b128 v[196:199], v157 offset:35840
	ds_read_b128 v[200:203], v157 offset:36864
	ds_read_b128 v[204:207], v157 offset:37888
	ds_read_b128 v[208:211], v157 offset:38912
	ds_read_b128 v[212:215], v157 offset:39936
	global_load_lds_dwordx4 v134, s[48:49]
	s_mov_b32 m0, s29
	s_nop 0
	global_load_lds_dwordx4 v130, s[48:49]
	s_mov_b32 m0, s23
	s_nop 0
	global_load_lds_dwordx4 v134, s[52:53]
	s_mov_b32 m0, s24
	s_nop 0
	global_load_lds_dwordx4 v130, s[52:53]
	s_nop 0
	s_waitcnt vmcnt(8)
	s_waitcnt lgkmcnt(0)
	s_barrier
	s_waitcnt lgkmcnt(0)
	v_mfma_f32_16x16x32_bf16 v[112:115], v[144:147], v[184:187], v[112:115]
	v_mfma_f32_16x16x32_bf16 v[108:111], v[160:163], v[184:187], v[108:111]
	v_mfma_f32_16x16x32_bf16 v[104:107], v[144:147], v[192:195], v[104:107]
	v_mfma_f32_16x16x32_bf16 v[100:103], v[160:163], v[192:195], v[100:103]
	v_mfma_f32_16x16x32_bf16 v[92:95], v[144:147], v[200:203], v[92:95]
	v_mfma_f32_16x16x32_bf16 v[84:87], v[160:163], v[200:203], v[84:87]
	v_mfma_f32_16x16x32_bf16 v[76:79], v[144:147], v[208:211], v[76:79]
	v_mfma_f32_16x16x32_bf16 v[68:71], v[160:163], v[208:211], v[68:71]
	v_mfma_f32_16x16x32_bf16 v[112:115], v[148:151], v[188:191], v[112:115]
	v_mfma_f32_16x16x32_bf16 v[108:111], v[164:167], v[188:191], v[108:111]
	v_mfma_f32_16x16x32_bf16 v[104:107], v[148:151], v[196:199], v[104:107]
	v_mfma_f32_16x16x32_bf16 v[100:103], v[164:167], v[196:199], v[100:103]
	v_mfma_f32_16x16x32_bf16 v[92:95], v[148:151], v[204:207], v[92:95]
	v_mfma_f32_16x16x32_bf16 v[84:87], v[164:167], v[204:207], v[84:87]
	v_mfma_f32_16x16x32_bf16 v[76:79], v[148:151], v[212:215], v[76:79]
	v_mfma_f32_16x16x32_bf16 v[68:71], v[164:167], v[212:215], v[68:71]
	v_mfma_f32_16x16x32_bf16 v[124:127], v[168:171], v[184:187], v[124:127]
	v_mfma_f32_16x16x32_bf16 v[120:123], v[176:179], v[184:187], v[120:123]
	v_mfma_f32_16x16x32_bf16 v[116:119], v[168:171], v[192:195], v[116:119]
	v_mfma_f32_16x16x32_bf16 v[96:99], v[176:179], v[192:195], v[96:99]
	v_mfma_f32_16x16x32_bf16 v[88:91], v[168:171], v[200:203], v[88:91]
	v_mfma_f32_16x16x32_bf16 v[80:83], v[176:179], v[200:203], v[80:83]
	v_mfma_f32_16x16x32_bf16 v[72:75], v[168:171], v[208:211], v[72:75]
	v_mfma_f32_16x16x32_bf16 v[64:67], v[176:179], v[208:211], v[64:67]
	v_mfma_f32_16x16x32_bf16 v[124:127], v[172:175], v[188:191], v[124:127]
	v_mfma_f32_16x16x32_bf16 v[120:123], v[180:183], v[188:191], v[120:123]
	v_mfma_f32_16x16x32_bf16 v[116:119], v[172:175], v[196:199], v[116:119]
	v_mfma_f32_16x16x32_bf16 v[96:99], v[180:183], v[196:199], v[96:99]
	v_mfma_f32_16x16x32_bf16 v[88:91], v[172:175], v[204:207], v[88:91]
	v_mfma_f32_16x16x32_bf16 v[80:83], v[180:183], v[204:207], v[80:83]
	v_mfma_f32_16x16x32_bf16 v[72:75], v[172:175], v[212:215], v[72:75]
	v_mfma_f32_16x16x32_bf16 v[64:67], v[180:183], v[212:215], v[64:67]
	s_barrier
	s_add_i32 s48, s67, s17
	s_mov_b32 m0, s48
	s_add_u32 s98, s50, 0x80
	s_addc_u32 s99, s51, 0
	ds_read_b128 v[184:187], v157 offset:49152
	ds_read_b128 v[188:191], v157 offset:50176
	ds_read_b128 v[192:195], v157 offset:51200
	ds_read_b128 v[196:199], v157 offset:52224
	ds_read_b128 v[200:203], v157 offset:53248
	ds_read_b128 v[204:207], v157 offset:54272
	ds_read_b128 v[208:211], v157 offset:55296
	ds_read_b128 v[212:215], v157 offset:56320
	global_load_lds_dwordx4 v132, s[98:99]
	s_add_i32 m0, s48, 0x2000
	s_add_u32 s48, s50, 0x104080
	s_addc_u32 s49, s51, 0
	s_add_i32 s50, s68, s17
	global_load_lds_dwordx4 v128, s[98:99]
	s_mov_b32 m0, s50
	s_nop 0
	global_load_lds_dwordx4 v132, s[48:49]
	s_add_i32 m0, s50, 0x2000
	s_nop 0
	global_load_lds_dwordx4 v128, s[48:49]
	s_nop 0
	s_waitcnt vmcnt(4)
	s_waitcnt lgkmcnt(0)
	s_barrier
	s_waitcnt lgkmcnt(0)
	v_mfma_f32_16x16x32_bf16 v[60:63], v[144:147], v[184:187], v[60:63]
	v_mfma_f32_16x16x32_bf16 v[52:55], v[160:163], v[184:187], v[52:55]
	v_mfma_f32_16x16x32_bf16 v[44:47], v[144:147], v[192:195], v[44:47]
	v_mfma_f32_16x16x32_bf16 v[36:39], v[160:163], v[192:195], v[36:39]
	v_mfma_f32_16x16x32_bf16 v[28:31], v[144:147], v[200:203], v[28:31]
	v_mfma_f32_16x16x32_bf16 v[20:23], v[160:163], v[200:203], v[20:23]
	v_mfma_f32_16x16x32_bf16 v[12:15], v[144:147], v[208:211], v[12:15]
	v_mfma_f32_16x16x32_bf16 v[4:7], v[160:163], v[208:211], v[4:7]
	v_mfma_f32_16x16x32_bf16 v[60:63], v[148:151], v[188:191], v[60:63]
	v_mfma_f32_16x16x32_bf16 v[52:55], v[164:167], v[188:191], v[52:55]
	v_mfma_f32_16x16x32_bf16 v[44:47], v[148:151], v[196:199], v[44:47]
	v_mfma_f32_16x16x32_bf16 v[36:39], v[164:167], v[196:199], v[36:39]
	v_mfma_f32_16x16x32_bf16 v[28:31], v[148:151], v[204:207], v[28:31]
	v_mfma_f32_16x16x32_bf16 v[20:23], v[164:167], v[204:207], v[20:23]
	v_mfma_f32_16x16x32_bf16 v[12:15], v[148:151], v[212:215], v[12:15]
	v_mfma_f32_16x16x32_bf16 v[4:7], v[164:167], v[212:215], v[4:7]
	v_mfma_f32_16x16x32_bf16 v[56:59], v[168:171], v[184:187], v[56:59]
	v_mfma_f32_16x16x32_bf16 v[48:51], v[176:179], v[184:187], v[48:51]
	v_mfma_f32_16x16x32_bf16 v[40:43], v[168:171], v[192:195], v[40:43]
	v_mfma_f32_16x16x32_bf16 v[32:35], v[176:179], v[192:195], v[32:35]
	v_mfma_f32_16x16x32_bf16 v[24:27], v[168:171], v[200:203], v[24:27]
	v_mfma_f32_16x16x32_bf16 v[16:19], v[176:179], v[200:203], v[16:19]
	v_mfma_f32_16x16x32_bf16 v[8:11], v[168:171], v[208:211], v[8:11]
	v_mfma_f32_16x16x32_bf16 v[0:3], v[176:179], v[208:211], v[0:3]
	v_mfma_f32_16x16x32_bf16 v[56:59], v[172:175], v[188:191], v[56:59]
	v_mfma_f32_16x16x32_bf16 v[48:51], v[180:183], v[188:191], v[48:51]
	v_mfma_f32_16x16x32_bf16 v[40:43], v[172:175], v[196:199], v[40:43]
	v_mfma_f32_16x16x32_bf16 v[32:35], v[180:183], v[196:199], v[32:35]
	v_mfma_f32_16x16x32_bf16 v[24:27], v[172:175], v[204:207], v[24:27]
	v_mfma_f32_16x16x32_bf16 v[16:19], v[180:183], v[204:207], v[16:19]
	v_mfma_f32_16x16x32_bf16 v[8:11], v[172:175], v[212:215], v[8:11]
	v_mfma_f32_16x16x32_bf16 v[0:3], v[180:183], v[212:215], v[0:3]
	s_barrier
	s_add_i32 s66, s66, 2
	s_add_u32 s64, s64, 0x100
	s_addc_u32 s65, s65, 0
	s_cmp_gt_u32 s66, 61
	s_mov_b64 s[48:49], s[4:5]
	s_cbranch_scc0 .LBB0_233
	s_and_b64 vcc, exec, s[42:43]
	s_cbranch_vccz .LBB0_236
	s_barrier
